# attention softmax row reductions: 32 ds_bpermute round trips per step replaced by DPP moves (quad_perm / row_half_mirror / row_mirror)
# baseline (speedup 1.0000x reference)
.LBB0_101:
	v_mov_b32_e32 v142, v124
	v_mov_b32_e32 v96, v173
	v_mov_b32_e32 v100, v173
	v_mov_b32_e32 v104, v173
	v_mov_b32_e32 v108, v173
	v_mov_b32_e32 v112, v173
	v_mov_b32_e32 v116, v173
	v_mov_b32_e32 v120, v173
	v_mov_b32_e32 v124, v173
	v_add_u32_e32 v133, v150, v155
	ds_read_b128 v[138:141], v133
	ds_read_b128 v[214:217], v209
	ds_read_b128 v[218:221], v209 offset:4352
	ds_read_b128 v[234:237], v209 offset:8704
	ds_read_b128 v[238:241], v209 offset:13056
	ds_read_b128 v[242:245], v209 offset:17408
	ds_read_b128 v[246:249], v209 offset:21760
	ds_read_b128 v[250:253], v209 offset:26112
	v_mov_b32_e32 v230, v125
	v_mov_b32_e32 v213, v98
	v_mov_b32_e32 v212, v99
	s_cmp_eq_u32 s20, s42
	v_mov_b32_e32 v98, v96
	v_mov_b32_e32 v99, v96
	v_mov_b32_e32 v125, v124
	s_cselect_b64 vcc, -1, 0
	v_mov_b32_e32 v97, v96
	v_mov_b32_e32 v101, v100
	v_mov_b32_e32 v102, v100
	v_mov_b32_e32 v103, v100
	v_mov_b32_e32 v105, v104
	v_mov_b32_e32 v106, v104
	v_mov_b32_e32 v107, v104
	v_mov_b32_e32 v109, v108
	v_mov_b32_e32 v110, v108
	v_mov_b32_e32 v111, v108
	v_mov_b32_e32 v113, v112
	v_mov_b32_e32 v114, v112
	v_mov_b32_e32 v115, v112
	v_mov_b32_e32 v117, v116
	v_mov_b32_e32 v118, v116
	v_mov_b32_e32 v119, v116
	v_mov_b32_e32 v121, v120
	v_mov_b32_e32 v122, v120
	v_mov_b32_e32 v123, v120
	v_mov_b32_e32 v126, v124
	v_mov_b32_e32 v127, v124
	s_waitcnt lgkmcnt(7)
	v_mfma_f32_16x16x32_bf16 v[96:99], v[60:63], v[138:141], v[96:99]
	s_waitcnt lgkmcnt(6)
	v_mfma_f32_16x16x32_bf16 v[100:103], v[60:63], v[214:217], v[100:103]
	s_waitcnt lgkmcnt(5)
	v_mfma_f32_16x16x32_bf16 v[104:107], v[60:63], v[218:221], v[104:107]
	s_waitcnt lgkmcnt(4)
	v_mfma_f32_16x16x32_bf16 v[108:111], v[60:63], v[234:237], v[108:111]
	s_waitcnt lgkmcnt(3)
	v_mfma_f32_16x16x32_bf16 v[112:115], v[60:63], v[238:241], v[112:115]
	s_waitcnt lgkmcnt(2)
	v_mfma_f32_16x16x32_bf16 v[116:119], v[60:63], v[242:245], v[116:119]
	s_waitcnt lgkmcnt(1)
	v_mfma_f32_16x16x32_bf16 v[120:123], v[60:63], v[246:249], v[120:123]
	s_waitcnt lgkmcnt(0)
	v_mfma_f32_16x16x32_bf16 v[124:127], v[60:63], v[250:253], v[124:127]
	ds_read_b128 v[138:141], v133 offset:64
	ds_read_b128 v[214:217], v209 offset:64
	ds_read_b128 v[218:221], v209 offset:4416
	ds_read_b128 v[234:237], v209 offset:8768
	ds_read_b128 v[238:241], v209 offset:13120
	ds_read_b128 v[242:245], v209 offset:17472
	ds_read_b128 v[246:249], v209 offset:21824
	ds_read_b128 v[250:253], v209 offset:26176
	s_waitcnt lgkmcnt(7)
	v_mfma_f32_16x16x32_bf16 v[96:99], v[56:59], v[138:141], v[96:99]
	s_waitcnt lgkmcnt(6)
	v_mfma_f32_16x16x32_bf16 v[100:103], v[56:59], v[214:217], v[100:103]
	s_waitcnt lgkmcnt(5)
	v_mfma_f32_16x16x32_bf16 v[104:107], v[56:59], v[218:221], v[104:107]
	s_waitcnt lgkmcnt(4)
	v_mfma_f32_16x16x32_bf16 v[108:111], v[56:59], v[234:237], v[108:111]
	s_waitcnt lgkmcnt(3)
	v_mfma_f32_16x16x32_bf16 v[112:115], v[56:59], v[238:241], v[112:115]
	s_waitcnt lgkmcnt(2)
	v_mfma_f32_16x16x32_bf16 v[116:119], v[56:59], v[242:245], v[116:119]
	s_waitcnt lgkmcnt(1)
	v_mfma_f32_16x16x32_bf16 v[120:123], v[56:59], v[246:249], v[120:123]
	s_waitcnt lgkmcnt(0)
	v_mfma_f32_16x16x32_bf16 v[124:127], v[56:59], v[250:253], v[124:127]
	ds_read_b128 v[138:141], v133 offset:128
	ds_read_b128 v[214:217], v209 offset:128
	ds_read_b128 v[218:221], v209 offset:4480
	ds_read_b128 v[234:237], v209 offset:8832
	ds_read_b128 v[238:241], v209 offset:13184
	ds_read_b128 v[242:245], v209 offset:17536
	ds_read_b128 v[246:249], v209 offset:21888
	ds_read_b128 v[250:253], v209 offset:26240
	s_waitcnt lgkmcnt(7)
	v_mfma_f32_16x16x32_bf16 v[96:99], v[52:55], v[138:141], v[96:99]
	s_waitcnt lgkmcnt(6)
	v_mfma_f32_16x16x32_bf16 v[100:103], v[52:55], v[214:217], v[100:103]
	s_waitcnt lgkmcnt(5)
	v_mfma_f32_16x16x32_bf16 v[104:107], v[52:55], v[218:221], v[104:107]
	s_waitcnt lgkmcnt(4)
	v_mfma_f32_16x16x32_bf16 v[108:111], v[52:55], v[234:237], v[108:111]
	s_waitcnt lgkmcnt(3)
	v_mfma_f32_16x16x32_bf16 v[112:115], v[52:55], v[238:241], v[112:115]
	s_waitcnt lgkmcnt(2)
	v_mfma_f32_16x16x32_bf16 v[116:119], v[52:55], v[242:245], v[116:119]
	s_waitcnt lgkmcnt(1)
	v_mfma_f32_16x16x32_bf16 v[120:123], v[52:55], v[246:249], v[120:123]
	s_waitcnt lgkmcnt(0)
	v_mfma_f32_16x16x32_bf16 v[124:127], v[52:55], v[250:253], v[124:127]
	ds_read_b128 v[138:141], v133 offset:192
	ds_read_b128 v[214:217], v209 offset:192
	ds_read_b128 v[218:221], v209 offset:4544
	ds_read_b128 v[234:237], v209 offset:8896
	ds_read_b128 v[238:241], v209 offset:13248
	ds_read_b128 v[242:245], v209 offset:17600
	ds_read_b128 v[246:249], v209 offset:21952
	ds_read_b128 v[250:253], v209 offset:26304
	s_waitcnt lgkmcnt(7)
	v_mfma_f32_16x16x32_bf16 v[96:99], v[48:51], v[138:141], v[96:99]
	v_sub_u32_e32 v138, 0, v160
	v_cndmask_b32_e32 v138, v138, v160, vcc
	v_cmp_lt_i32_e64 s[42:43], -1, v138
	s_waitcnt lgkmcnt(6)
	v_mfma_f32_16x16x32_bf16 v[100:103], v[48:51], v[214:217], v[100:103]
	v_sub_u32_e32 v138, 0, v161
	v_cndmask_b32_e32 v138, v138, v161, vcc
	v_sub_u32_e32 v139, 0, v162
	s_waitcnt lgkmcnt(5)
	v_mfma_f32_16x16x32_bf16 v[104:107], v[48:51], v[218:221], v[104:107]
	v_cndmask_b32_e64 v96, v224, v96, s[42:43]
	v_cmp_lt_i32_e64 s[42:43], -1, v138
	v_cndmask_b32_e32 v139, v139, v162, vcc
	s_waitcnt lgkmcnt(4)
	v_mfma_f32_16x16x32_bf16 v[108:111], v[48:51], v[234:237], v[108:111]
	v_cndmask_b32_e64 v100, v224, v100, s[42:43]
	v_cmp_lt_i32_e64 s[42:43], -1, v139
	v_sub_u32_e32 v139, 0, v163
	v_cndmask_b32_e32 v139, v139, v163, vcc
	v_cndmask_b32_e64 v104, v224, v104, s[42:43]
	s_waitcnt lgkmcnt(3)
	v_mfma_f32_16x16x32_bf16 v[112:115], v[48:51], v[238:241], v[112:115]
	v_cmp_lt_i32_e64 s[42:43], -1, v139
	v_sub_u32_e32 v139, 0, v164
	v_cndmask_b32_e32 v139, v139, v164, vcc
	v_cndmask_b32_e64 v108, v224, v108, s[42:43]
	s_waitcnt lgkmcnt(2)
	v_mfma_f32_16x16x32_bf16 v[116:119], v[48:51], v[242:245], v[116:119]
	v_cmp_lt_i32_e64 s[42:43], -1, v139
	v_sub_u32_e32 v139, 0, v165
	v_cndmask_b32_e32 v139, v139, v165, vcc
	v_cndmask_b32_e64 v112, v224, v112, s[42:43]
	s_waitcnt lgkmcnt(1)
	v_mfma_f32_16x16x32_bf16 v[120:123], v[48:51], v[246:249], v[120:123]
	v_cmp_lt_i32_e64 s[42:43], -1, v139
	v_sub_u32_e32 v139, 0, v166
	v_cndmask_b32_e32 v139, v139, v166, vcc
	s_waitcnt lgkmcnt(0)
	v_mfma_f32_16x16x32_bf16 v[124:127], v[48:51], v[250:253], v[124:127]
	s_mov_b32 s4, 0xf149f2ca
	v_cndmask_b32_e64 v116, v224, v116, s[42:43]
	v_cmp_lt_i32_e64 s[42:43], -1, v139
	v_sub_u32_e32 v139, 0, v167
	v_max3_f32 v138, v96, s4, v100
	v_cndmask_b32_e32 v139, v139, v167, vcc
	v_max3_f32 v138, v138, v104, v108
	v_cndmask_b32_e64 v120, v224, v120, s[42:43]
	v_cmp_lt_i32_e64 s[42:43], -1, v139
	v_max3_f32 v138, v138, v112, v116
	s_nop 0
	v_cndmask_b32_e64 v140, v224, v124, s[42:43]
	v_max3_f32 v124, v138, v120, v140
	s_nop 1
	v_mov_b32_dpp v138, v124 quad_perm:[1,0,3,2] row_mask:0xf bank_mask:0xf
	v_max_f32_e32 v138, v138, v138
	v_max_f32_e32 v124, v124, v138
	s_nop 1
	v_mov_b32_dpp v138, v124 quad_perm:[2,3,0,1] row_mask:0xf bank_mask:0xf
	v_max_f32_e32 v138, v138, v138
	v_max_f32_e32 v124, v124, v138
	s_nop 1
	v_mov_b32_dpp v138, v124 row_half_mirror row_mask:0xf bank_mask:0xf
	v_max_f32_e32 v138, v138, v138
	v_max_f32_e32 v124, v124, v138
	s_nop 1
	v_mov_b32_dpp v138, v124 row_mirror row_mask:0xf bank_mask:0xf
	v_max3_f32 v124, v142, v124, v138
	v_sub_f32_e32 v96, v96, v124
	v_mul_f32_e32 v96, 0x3fb8aa3b, v96
	v_exp_f32_e32 v141, v96
	v_sub_f32_e32 v96, v100, v124
	v_sub_u32_e32 v100, 0, v168
	v_cndmask_b32_e32 v100, v100, v168, vcc
	v_cmp_lt_i32_e64 s[42:43], -1, v100
	v_mul_f32_e32 v96, 0x3fb8aa3b, v96
	v_exp_f32_e32 v139, v96
	v_cndmask_b32_e64 v100, v224, v97, s[42:43]
	v_sub_u32_e32 v97, 0, v169
	v_cndmask_b32_e32 v97, v97, v169, vcc
	v_cmp_lt_i32_e64 s[42:43], -1, v97
	v_sub_f32_e32 v96, v104, v124
	v_sub_f32_e32 v138, v142, v124
	v_cndmask_b32_e64 v104, v224, v101, s[42:43]
	v_sub_u32_e32 v101, 0, v170
	v_cndmask_b32_e32 v101, v101, v170, vcc
	v_cmp_lt_i32_e64 s[42:43], -1, v101
	v_sub_u32_e32 v101, 0, v171
	v_cndmask_b32_e32 v101, v101, v171, vcc
	v_cndmask_b32_e64 v142, v224, v105, s[42:43]
	v_cmp_lt_i32_e64 s[42:43], -1, v101
	v_sub_u32_e32 v101, 0, v179
	v_cndmask_b32_e32 v101, v101, v179, vcc
	v_cndmask_b32_e64 v214, v224, v109, s[42:43]
	v_cmp_lt_i32_e64 s[42:43], -1, v101
	v_sub_u32_e32 v101, 0, v182
	v_cndmask_b32_e32 v101, v101, v182, vcc
	v_cndmask_b32_e64 v215, v224, v113, s[42:43]
	v_cmp_lt_i32_e64 s[42:43], -1, v101
	v_sub_u32_e32 v101, 0, v183
	v_cndmask_b32_e32 v101, v101, v183, vcc
	v_cndmask_b32_e64 v216, v224, v117, s[42:43]
	v_cmp_lt_i32_e64 s[42:43], -1, v101
	v_sub_u32_e32 v101, 0, v184
	v_max3_f32 v97, v100, s4, v104
	v_cndmask_b32_e32 v101, v101, v184, vcc
	v_max3_f32 v97, v97, v142, v214
	v_cndmask_b32_e64 v217, v224, v121, s[42:43]
	v_cmp_lt_i32_e64 s[42:43], -1, v101
	v_max3_f32 v97, v97, v215, v216
	v_mul_f32_e32 v96, 0x3fb8aa3b, v96
	v_cndmask_b32_e64 v218, v224, v125, s[42:43]
	v_max3_f32 v97, v97, v217, v218
	s_nop 1
	v_mov_b32_dpp v101, v97 quad_perm:[1,0,3,2] row_mask:0xf bank_mask:0xf
	v_exp_f32_e32 v117, v96
	v_sub_f32_e32 v96, v108, v124
	v_mul_f32_e32 v96, 0x3fb8aa3b, v96
	v_exp_f32_e32 v113, v96
	v_max_f32_e32 v101, v101, v101
	v_max_f32_e32 v97, v97, v101
	s_nop 1
	v_mov_b32_dpp v101, v97 quad_perm:[2,3,0,1] row_mask:0xf bank_mask:0xf
	v_sub_f32_e32 v96, v112, v124
	v_mul_f32_e32 v96, 0x3fb8aa3b, v96
	v_exp_f32_e32 v105, v96
	v_sub_f32_e32 v108, v120, v124
	v_max_f32_e32 v96, v101, v101
	v_max_f32_e32 v96, v97, v96
	s_nop 1
	v_mov_b32_dpp v97, v96 row_half_mirror row_mask:0xf bank_mask:0xf
	v_mul_f32_e32 v138, 0x3fb8aa3b, v138
	v_exp_f32_e32 v143, v138
	v_sub_f32_e32 v101, v116, v124
	v_mul_f32_e32 v101, 0x3fb8aa3b, v101
	v_max_f32_e32 v97, v97, v97
	v_max_f32_e32 v96, v96, v97
	s_nop 1
	v_mov_b32_dpp v109, v96 row_mirror row_mask:0xf bank_mask:0xf
	v_mul_f32_e32 v97, 0x3fb8aa3b, v108
	v_sub_f32_e32 v108, v140, v124
	v_mul_f32_e32 v108, 0x3fb8aa3b, v108
	v_exp_f32_e32 v101, v101
	v_max3_f32 v125, v230, v96, v109
	v_sub_f32_e32 v96, v100, v125
	v_mul_f32_e32 v96, 0x3fb8aa3b, v96
	v_exp_f32_e32 v109, v108
	v_sub_u32_e32 v108, 0, v185
	v_exp_f32_e32 v140, v96
	v_sub_f32_e32 v96, v104, v125
	v_cndmask_b32_e32 v108, v108, v185, vcc
	v_mul_f32_e32 v96, 0x3fb8aa3b, v96
	v_cmp_lt_i32_e64 s[42:43], -1, v108
	v_exp_f32_e32 v138, v96
	v_sub_f32_e32 v96, v142, v125
	v_cndmask_b32_e64 v142, v224, v98, s[42:43]
	v_sub_u32_e32 v98, 0, v186
	v_cndmask_b32_e32 v98, v98, v186, vcc
	v_sub_u32_e32 v108, 0, v187
	v_cmp_lt_i32_e64 s[42:43], -1, v98
	v_cndmask_b32_e32 v108, v108, v187, vcc
	v_mul_f32_e32 v96, 0x3fb8aa3b, v96
	v_cndmask_b32_e64 v102, v224, v102, s[42:43]
	v_cmp_lt_i32_e64 s[42:43], -1, v108
	v_sub_u32_e32 v108, 0, v188
	v_cndmask_b32_e32 v108, v108, v188, vcc
	v_cndmask_b32_e64 v106, v224, v106, s[42:43]
	v_cmp_lt_i32_e64 s[42:43], -1, v108
	v_sub_u32_e32 v108, 0, v189
	v_cndmask_b32_e32 v108, v108, v189, vcc
	v_cndmask_b32_e64 v110, v224, v110, s[42:43]
	v_cmp_lt_i32_e64 s[42:43], -1, v108
	v_sub_u32_e32 v108, 0, v190
	v_cndmask_b32_e32 v108, v108, v190, vcc
	v_cndmask_b32_e64 v114, v224, v114, s[42:43]
	v_cmp_lt_i32_e64 s[42:43], -1, v108
	v_sub_u32_e32 v108, 0, v192
	v_cndmask_b32_e32 v108, v108, v192, vcc
	v_cndmask_b32_e64 v118, v224, v118, s[42:43]
	v_cmp_lt_i32_e64 s[42:43], -1, v108
	v_sub_u32_e32 v108, 0, v194
	v_max3_f32 v98, v142, s4, v102
	v_cndmask_b32_e32 v108, v108, v194, vcc
	v_max3_f32 v98, v98, v106, v110
	v_cndmask_b32_e64 v122, v224, v122, s[42:43]
	v_cmp_lt_i32_e64 s[42:43], -1, v108
	v_max3_f32 v98, v98, v114, v118
	v_exp_f32_e32 v116, v96
	v_cndmask_b32_e64 v126, v224, v126, s[42:43]
	v_max3_f32 v98, v98, v122, v126
	s_nop 1
	v_mov_b32_dpp v108, v98 quad_perm:[1,0,3,2] row_mask:0xf bank_mask:0xf
	v_sub_f32_e32 v96, v214, v125
	v_mul_f32_e32 v96, 0x3fb8aa3b, v96
	v_exp_f32_e32 v112, v96
	v_sub_f32_e32 v96, v215, v125
	v_max_f32_e32 v108, v108, v108
	v_max_f32_e32 v98, v98, v108
	s_nop 1
	v_mov_b32_dpp v215, v98 quad_perm:[2,3,0,1] row_mask:0xf bank_mask:0xf
	v_sub_f32_e32 v214, v218, v125
	v_mul_f32_e32 v214, 0x3fb8aa3b, v214
	v_exp_f32_e32 v108, v214
	v_mul_f32_e32 v96, 0x3fb8aa3b, v96
	v_max_f32_e32 v214, v215, v215
	v_max_f32_e32 v98, v98, v214
	v_exp_f32_e32 v104, v96
	v_sub_f32_e32 v96, v216, v125
	s_nop 1
	v_mov_b32_dpp v216, v98 row_half_mirror row_mask:0xf bank_mask:0xf
	v_mul_f32_e32 v96, 0x3fb8aa3b, v96
	v_pk_add_f32 v[120:121], v[140:141], 0 op_sel_hi:[1,0]
	v_exp_f32_e32 v100, v96
	v_sub_f32_e32 v96, v217, v125
	v_pk_add_f32 v[120:121], v[138:139], v[120:121]
	v_mul_f32_e32 v96, 0x3fb8aa3b, v96
	v_exp_f32_e32 v97, v97
	v_pk_add_f32 v[120:121], v[116:117], v[120:121]
	v_exp_f32_e32 v96, v96
	v_pk_add_f32 v[120:121], v[112:113], v[120:121]
	v_max_f32_e32 v216, v216, v216
	v_pk_add_f32 v[120:121], v[104:105], v[120:121]
	v_max_f32_e32 v98, v98, v216
	v_pk_add_f32 v[120:121], v[100:101], v[120:121]
	s_nop 1
	v_mov_b32_dpp v218, v98 row_mirror row_mask:0xf bank_mask:0xf
	v_pk_add_f32 v[120:121], v[96:97], v[120:121]
	v_cvt_pk_bf16_f32 v96, v96, s0
	v_pk_add_f32 v[120:121], v[108:109], v[120:121]
	s_nop 1
	v_mov_b32_dpp v215, v121 quad_perm:[1,0,3,2] row_mask:0xf bank_mask:0xf
	s_nop 1
	v_mov_b32_dpp v214, v120 quad_perm:[1,0,3,2] row_mask:0xf bank_mask:0xf
	v_max3_f32 v98, v213, v98, v218
	v_sub_f32_e32 v102, v102, v98
	v_mul_f32_e32 v102, 0x3fb8aa3b, v102
	v_sub_f32_e32 v230, v230, v125
	v_pk_add_f32 v[214:215], v[120:121], v[214:215]
	v_exp_f32_e32 v121, v102
	v_sub_f32_e32 v102, v106, v98
	v_sub_u32_e32 v106, 0, v196
	v_cndmask_b32_e32 v106, v106, v196, vcc
	v_cmp_lt_i32_e64 s[42:43], -1, v106
	v_sub_f32_e32 v120, v142, v98
	v_mul_f32_e32 v120, 0x3fb8aa3b, v120
	v_cndmask_b32_e64 v106, v224, v99, s[42:43]
	v_sub_u32_e32 v99, 0, v197
	v_cndmask_b32_e32 v99, v99, v197, vcc
	v_cmp_lt_i32_e64 s[42:43], -1, v99
	v_exp_f32_e32 v219, v120
	v_mul_f32_e32 v102, 0x3fb8aa3b, v102
	v_cndmask_b32_e64 v120, v224, v103, s[42:43]
	v_sub_u32_e32 v103, 0, v198
	v_cndmask_b32_e32 v103, v103, v198, vcc
	v_cmp_lt_i32_e64 s[42:43], -1, v103
	v_sub_u32_e32 v103, 0, v199
	v_cndmask_b32_e32 v103, v103, v199, vcc
	v_cndmask_b32_e64 v142, v224, v107, s[42:43]
	v_cmp_lt_i32_e64 s[42:43], -1, v103
	v_sub_u32_e32 v103, 0, v200
	v_cndmask_b32_e32 v103, v103, v200, vcc
	v_cndmask_b32_e64 v220, v224, v111, s[42:43]
	v_cmp_lt_i32_e64 s[42:43], -1, v103
	v_sub_u32_e32 v103, 0, v201
	v_cndmask_b32_e32 v103, v103, v201, vcc
	v_cndmask_b32_e64 v221, v224, v115, s[42:43]
	v_cmp_lt_i32_e64 s[42:43], -1, v103
	v_sub_u32_e32 v103, 0, v202
	v_cndmask_b32_e32 v103, v103, v202, vcc
	v_cndmask_b32_e64 v231, v224, v119, s[42:43]
	v_cmp_lt_i32_e64 s[42:43], -1, v103
	v_sub_u32_e32 v103, 0, v203
	v_max3_f32 v99, v106, s4, v120
	v_cndmask_b32_e32 v103, v103, v203, vcc
	v_max3_f32 v99, v99, v142, v220
	v_cndmask_b32_e64 v233, v224, v123, s[42:43]
	v_cmp_lt_i32_e64 s[42:43], -1, v103
	v_max3_f32 v99, v99, v221, v231
	v_exp_f32_e32 v103, v102
	v_cndmask_b32_e64 v234, v224, v127, s[42:43]
	v_max3_f32 v99, v99, v233, v234
	s_nop 1
	v_mov_b32_dpp v107, v99 quad_perm:[1,0,3,2] row_mask:0xf bank_mask:0xf
	v_sub_f32_e32 v102, v110, v98
	v_mul_f32_e32 v102, 0x3fb8aa3b, v102
	s_nop 1
	v_mov_b32_dpp v217, v215 quad_perm:[2,3,0,1] row_mask:0xf bank_mask:0xf
	s_nop 1
	v_mov_b32_dpp v216, v214 quad_perm:[2,3,0,1] row_mask:0xf bank_mask:0xf
	v_max_f32_e32 v107, v107, v107
	v_max_f32_e32 v99, v99, v107
	s_nop 1
	v_mov_b32_dpp v110, v99 quad_perm:[2,3,0,1] row_mask:0xf bank_mask:0xf
	v_exp_f32_e32 v107, v102
	v_sub_f32_e32 v102, v114, v98
	v_mul_f32_e32 v102, 0x3fb8aa3b, v102
	v_exp_f32_e32 v111, v102
	v_max_f32_e32 v102, v110, v110
	v_max_f32_e32 v99, v99, v102
	s_nop 1
	v_mov_b32_dpp v102, v99 row_half_mirror row_mask:0xf bank_mask:0xf
	v_sub_f32_e32 v110, v118, v98
	v_mul_f32_e32 v110, 0x3fb8aa3b, v110
	v_exp_f32_e32 v115, v110
	v_sub_f32_e32 v110, v122, v98
	v_max_f32_e32 v102, v102, v102
	v_max_f32_e32 v99, v99, v102
	s_nop 1
	v_mov_b32_dpp v102, v99 row_mirror row_mask:0xf bank_mask:0xf
	v_mul_f32_e32 v110, 0x3fb8aa3b, v110
	v_exp_f32_e32 v119, v110
	v_sub_f32_e32 v110, v126, v98
	v_mul_f32_e32 v110, 0x3fb8aa3b, v110
	v_max3_f32 v99, v212, v99, v102
	v_sub_f32_e32 v102, v106, v99
	v_mul_f32_e32 v102, 0x3fb8aa3b, v102
	v_exp_f32_e32 v218, v102
	v_sub_f32_e32 v102, v120, v99
	v_mul_f32_e32 v102, 0x3fb8aa3b, v102
	v_exp_f32_e32 v120, v102
	v_sub_f32_e32 v102, v142, v99
	v_mul_f32_e32 v102, 0x3fb8aa3b, v102
	v_sub_f32_e32 v106, v220, v99
	v_exp_f32_e32 v102, v102
	v_exp_f32_e32 v123, v110
	v_mul_f32_e32 v106, 0x3fb8aa3b, v106
	v_sub_f32_e32 v110, v221, v99
	v_exp_f32_e32 v106, v106
	v_mul_f32_e32 v110, 0x3fb8aa3b, v110
	v_sub_f32_e32 v114, v231, v99
	v_pk_add_f32 v[126:127], v[218:219], 0 op_sel_hi:[1,0]
	v_exp_f32_e32 v110, v110
	v_mul_f32_e32 v114, 0x3fb8aa3b, v114
	v_sub_f32_e32 v118, v233, v99
	v_pk_add_f32 v[126:127], v[120:121], v[126:127]
	v_exp_f32_e32 v114, v114
	v_mul_f32_e32 v118, 0x3fb8aa3b, v118
	v_sub_f32_e32 v122, v234, v99
	v_pk_add_f32 v[126:127], v[102:103], v[126:127]
	v_exp_f32_e32 v118, v118
	v_mul_f32_e32 v122, 0x3fb8aa3b, v122
	v_exp_f32_e32 v122, v122
	v_pk_add_f32 v[126:127], v[106:107], v[126:127]
	v_pk_add_f32 v[214:215], v[214:215], v[216:217]
	v_pk_add_f32 v[126:127], v[110:111], v[126:127]
	s_nop 1
	v_mov_b32_dpp v217, v215 row_half_mirror row_mask:0xf bank_mask:0xf
	v_pk_add_f32 v[126:127], v[114:115], v[126:127]
	s_nop 1
	v_mov_b32_dpp v216, v214 row_half_mirror row_mask:0xf bank_mask:0xf
	v_pk_add_f32 v[126:127], v[118:119], v[126:127]
	v_cvt_pk_bf16_f32 v102, v102, s0
	v_pk_add_f32 v[126:127], v[122:123], v[126:127]
	s_nop 1
	v_mov_b32_dpp v221, v127 quad_perm:[1,0,3,2] row_mask:0xf bank_mask:0xf
	s_nop 1
	v_mov_b32_dpp v220, v126 quad_perm:[1,0,3,2] row_mask:0xf bank_mask:0xf
	ds_write_b16 v211, v102 offset:880
	v_cvt_pk_bf16_f32 v102, v113, s0
	v_pk_add_f32 v[214:215], v[214:215], v[216:217]
	ds_write_b16 v211, v102 offset:96
	v_pk_add_f32 v[126:127], v[126:127], v[220:221]
	s_nop 1
	v_mov_b32_dpp v221, v127 quad_perm:[2,3,0,1] row_mask:0xf bank_mask:0xf
	s_nop 1
	v_mov_b32_dpp v220, v126 quad_perm:[2,3,0,1] row_mask:0xf bank_mask:0xf
	v_cvt_pk_bf16_f32 v102, v112, s0
	s_nop 1
	v_mov_b32_dpp v217, v215 row_mirror row_mask:0xf bank_mask:0xf
	s_nop 1
	v_mov_b32_dpp v216, v214 row_mirror row_mask:0xf bank_mask:0xf
	v_sub_f32_e32 v213, v213, v98
	v_pk_add_f32 v[126:127], v[126:127], v[220:221]
	s_nop 1
	v_mov_b32_dpp v221, v127 row_half_mirror row_mask:0xf bank_mask:0xf
	s_nop 1
	v_mov_b32_dpp v220, v126 row_half_mirror row_mask:0xf bank_mask:0xf
	v_sub_f32_e32 v212, v212, v99
	ds_write_b16 v211, v102 offset:368
	v_cvt_pk_bf16_f32 v102, v107, s0
	ds_write_b16 v211, v96 offset:464
	v_pk_add_f32 v[126:127], v[126:127], v[220:221]
	s_nop 1
	v_mov_b32_dpp v221, v127 row_mirror row_mask:0xf bank_mask:0xf
	s_nop 1
	v_mov_b32_dpp v220, v126 row_mirror row_mask:0xf bank_mask:0xf
	v_cvt_pk_bf16_f32 v96, v119, s0
	v_mul_f32_e32 v142, 0x3fb8aa3b, v230
	v_mul_f32_e32 v213, 0x3fb8aa3b, v213
	v_mul_f32_e32 v212, 0x3fb8aa3b, v212
	ds_write_b16 v211, v102 offset:640
	v_cvt_pk_bf16_f32 v102, v106, s0
	ds_write_b16 v211, v96 offset:736
	v_cvt_pk_bf16_f32 v96, v118, s0
	v_exp_f32_e32 v142, v142
	v_exp_f32_e32 v213, v213
	v_exp_f32_e32 v212, v212
	ds_write_b16 v211, v102 offset:912
	v_cvt_pk_bf16_f32 v102, v105, s0
	ds_write_b16 v211, v96 offset:1008
	v_cvt_pk_bf16_f32 v96, v109, s0
	v_cvt_pk_bf16_f32 v140, v140, s0
	ds_write_b16 v211, v102 offset:128
	v_cvt_pk_bf16_f32 v102, v104, s0
	v_cvt_pk_bf16_f32 v100, v100, s0
	ds_write_b16 v211, v96 offset:224
	v_cvt_pk_bf16_f32 v96, v108, s0
	ds_write_b16 v211, v140 offset:272
	v_cvt_pk_bf16_f32 v140, v219, s0
	ds_write_b16 v211, v102 offset:400
	v_cvt_pk_bf16_f32 v102, v111, s0
	ds_write_b16 v211, v100 offset:432
	v_cvt_pk_bf16_f32 v100, v115, s0
	ds_write_b16 v211, v96 offset:496
	v_cvt_pk_bf16_f32 v96, v123, s0
	v_pk_add_f32 v[214:215], v[214:215], v[216:217]
	s_waitcnt lgkmcnt(10)
	v_pk_add_f32 v[126:127], v[126:127], v[220:221]
	v_cvt_pk_bf16_f32 v141, v141, s0
	ds_write_b16 v211, v140 offset:544
	v_cvt_pk_bf16_f32 v140, v218, s0
	v_cvt_pk_bf16_f32 v139, v139, s0
	v_cvt_pk_bf16_f32 v138, v138, s0
	v_cvt_pk_bf16_f32 v121, v121, s0
	v_cvt_pk_bf16_f32 v120, v120, s0
	v_cvt_pk_bf16_f32 v117, v117, s0
	v_cvt_pk_bf16_f32 v116, v116, s0
	v_cvt_pk_bf16_f32 v103, v103, s0
	ds_write_b16 v211, v102 offset:672
	v_cvt_pk_bf16_f32 v102, v110, s0
	v_cvt_pk_bf16_f32 v101, v101, s0
	ds_write_b16 v211, v100 offset:704
	v_cvt_pk_bf16_f32 v100, v114, s0
	v_cvt_pk_bf16_f32 v97, v97, s0
	ds_write_b16 v211, v96 offset:768
	v_cvt_pk_bf16_f32 v96, v122, s0
	v_pk_fma_f32 v[136:137], v[136:137], v[142:143], v[214:215]
	v_pk_fma_f32 v[134:135], v[134:135], v[212:213], v[126:127]
	v_mov_b32_e32 v126, v213
	v_mov_b32_e32 v127, v212
	ds_write_b16 v211, v141
	ds_write_b16 v211, v140 offset:816
	ds_write_b16 v211, v139 offset:32
	ds_write_b16 v211, v138 offset:304
	ds_write_b16 v211, v121 offset:576
	ds_write_b16 v211, v120 offset:848
	ds_write_b16 v211, v117 offset:64
	ds_write_b16 v211, v116 offset:336
	ds_write_b16 v211, v103 offset:608
	ds_write_b16 v211, v102 offset:944
	ds_write_b16 v211, v101 offset:160
	ds_write_b16 v211, v100 offset:976
	ds_write_b16 v211, v97 offset:192
	ds_write_b16 v211, v96 offset:1040
	ds_read_b128 v[100:103], v156
	ds_read_b128 v[104:107], v133 offset:34816
	ds_read_b128 v[108:111], v209 offset:34816
	ds_read_b128 v[112:115], v209 offset:39168
	ds_read_b128 v[116:119], v209 offset:43520
	ds_read_b128 v[120:123], v209 offset:47872
	ds_read_b128 v[138:141], v209 offset:52224
	ds_read_b128 v[212:215], v209 offset:56576
	ds_read_b128 v[216:219], v209 offset:60928
	v_mov_b32_e32 v220, v143
	v_mov_b32_e32 v221, v142
	v_pk_mul_f32 v[94:95], v[94:95], v[126:127]
	v_pk_mul_f32 v[92:93], v[92:93], v[220:221]
	v_pk_mul_f32 v[90:91], v[90:91], v[126:127]
	v_pk_mul_f32 v[88:89], v[88:89], v[220:221]
	v_pk_mul_f32 v[86:87], v[86:87], v[126:127]
	v_pk_mul_f32 v[84:85], v[84:85], v[220:221]
	v_pk_mul_f32 v[82:83], v[82:83], v[126:127]
	v_pk_mul_f32 v[80:81], v[80:81], v[220:221]
	v_pk_mul_f32 v[78:79], v[78:79], v[126:127]
	v_pk_mul_f32 v[76:77], v[76:77], v[220:221]
	v_pk_mul_f32 v[74:75], v[74:75], v[126:127]
	v_pk_mul_f32 v[72:73], v[72:73], v[220:221]
	v_pk_mul_f32 v[70:71], v[70:71], v[126:127]
	v_pk_mul_f32 v[68:69], v[68:69], v[220:221]
	v_pk_mul_f32 v[66:67], v[66:67], v[126:127]
	v_pk_mul_f32 v[64:65], v[64:65], v[220:221]
	s_waitcnt lgkmcnt(7)
	v_mfma_f32_16x16x32_bf16 v[92:95], v[100:103], v[104:107], v[92:95]
	s_waitcnt lgkmcnt(6)
	v_mfma_f32_16x16x32_bf16 v[88:91], v[100:103], v[108:111], v[88:91]
	s_waitcnt lgkmcnt(5)
	v_mfma_f32_16x16x32_bf16 v[84:87], v[100:103], v[112:115], v[84:87]
	s_waitcnt lgkmcnt(4)
	v_mfma_f32_16x16x32_bf16 v[80:83], v[100:103], v[116:119], v[80:83]
	s_waitcnt lgkmcnt(3)
	v_mfma_f32_16x16x32_bf16 v[76:79], v[100:103], v[120:123], v[76:79]
	s_waitcnt lgkmcnt(2)
	v_mfma_f32_16x16x32_bf16 v[72:75], v[100:103], v[138:141], v[72:75]
	s_waitcnt lgkmcnt(1)
	v_mfma_f32_16x16x32_bf16 v[68:71], v[100:103], v[212:215], v[68:71]
	s_waitcnt lgkmcnt(0)
	v_mfma_f32_16x16x32_bf16 v[64:67], v[100:103], v[216:219], v[64:67]
	ds_read_b128 v[100:103], v156 offset:64
	ds_read_b128 v[104:107], v133 offset:34880
	ds_read_b128 v[108:111], v209 offset:34880
	ds_read_b128 v[112:115], v209 offset:39232
	ds_read_b128 v[116:119], v209 offset:43584
	ds_read_b128 v[120:123], v209 offset:47936
	ds_read_b128 v[138:141], v209 offset:52288
	ds_read_b128 v[212:215], v209 offset:56640
	ds_read_b128 v[216:219], v209 offset:60992
	s_waitcnt lgkmcnt(7)
	v_mfma_f32_16x16x32_bf16 v[92:95], v[100:103], v[104:107], v[92:95]
	s_waitcnt lgkmcnt(6)
	v_mfma_f32_16x16x32_bf16 v[88:91], v[100:103], v[108:111], v[88:91]
	s_waitcnt lgkmcnt(5)
	v_mfma_f32_16x16x32_bf16 v[84:87], v[100:103], v[112:115], v[84:87]
	s_waitcnt lgkmcnt(4)
	v_mfma_f32_16x16x32_bf16 v[80:83], v[100:103], v[116:119], v[80:83]
	s_waitcnt lgkmcnt(3)
	v_mfma_f32_16x16x32_bf16 v[76:79], v[100:103], v[120:123], v[76:79]
	s_waitcnt lgkmcnt(2)
	v_mfma_f32_16x16x32_bf16 v[72:75], v[100:103], v[138:141], v[72:75]
	s_waitcnt lgkmcnt(1)
	v_mfma_f32_16x16x32_bf16 v[68:71], v[100:103], v[212:215], v[68:71]
	s_waitcnt lgkmcnt(0)
	v_mfma_f32_16x16x32_bf16 v[64:67], v[100:103], v[216:219], v[64:67]
	ds_read_b128 v[100:103], v156 offset:128
	ds_read_b128 v[104:107], v133 offset:34944
	ds_read_b128 v[108:111], v209 offset:34944
	ds_read_b128 v[112:115], v209 offset:39296
	ds_read_b128 v[116:119], v209 offset:43648
	ds_read_b128 v[120:123], v209 offset:48000
	ds_read_b128 v[138:141], v209 offset:52352
	ds_read_b128 v[212:215], v209 offset:56704
	ds_read_b128 v[216:219], v209 offset:61056
	s_waitcnt lgkmcnt(7)
	v_mfma_f32_16x16x32_bf16 v[92:95], v[100:103], v[104:107], v[92:95]
	s_waitcnt lgkmcnt(6)
	v_mfma_f32_16x16x32_bf16 v[88:91], v[100:103], v[108:111], v[88:91]
	s_waitcnt lgkmcnt(5)
	v_mfma_f32_16x16x32_bf16 v[84:87], v[100:103], v[112:115], v[84:87]
	s_waitcnt lgkmcnt(4)
	v_mfma_f32_16x16x32_bf16 v[80:83], v[100:103], v[116:119], v[80:83]
	s_waitcnt lgkmcnt(3)
	v_mfma_f32_16x16x32_bf16 v[76:79], v[100:103], v[120:123], v[76:79]
	s_waitcnt lgkmcnt(2)
	v_mfma_f32_16x16x32_bf16 v[72:75], v[100:103], v[138:141], v[72:75]
	s_waitcnt lgkmcnt(1)
	v_mfma_f32_16x16x32_bf16 v[68:71], v[100:103], v[212:215], v[68:71]
	s_waitcnt lgkmcnt(0)
	v_mfma_f32_16x16x32_bf16 v[64:67], v[100:103], v[216:219], v[64:67]
	ds_read_b128 v[100:103], v156 offset:192
	ds_read_b128 v[104:107], v133 offset:35008
	ds_read_b128 v[108:111], v209 offset:35008
	ds_read_b128 v[112:115], v209 offset:39360
	ds_read_b128 v[116:119], v209 offset:43712
	ds_read_b128 v[120:123], v209 offset:48064
	ds_read_b128 v[138:141], v209 offset:52416
	ds_read_b128 v[212:215], v209 offset:56768
	ds_read_b128 v[216:219], v209 offset:61120
	s_waitcnt lgkmcnt(7)
	v_mfma_f32_16x16x32_bf16 v[92:95], v[100:103], v[104:107], v[92:95]
	s_mov_b64 s[4:5], -1
	s_and_b64 vcc, exec, vcc
	s_waitcnt lgkmcnt(6)
	v_mfma_f32_16x16x32_bf16 v[88:91], v[100:103], v[108:111], v[88:91]
	s_waitcnt lgkmcnt(5)
	v_mfma_f32_16x16x32_bf16 v[84:87], v[100:103], v[112:115], v[84:87]
	s_waitcnt lgkmcnt(4)
	v_mfma_f32_16x16x32_bf16 v[80:83], v[100:103], v[116:119], v[80:83]
	s_waitcnt lgkmcnt(3)
	v_mfma_f32_16x16x32_bf16 v[76:79], v[100:103], v[120:123], v[76:79]
	s_waitcnt lgkmcnt(2)
	v_mfma_f32_16x16x32_bf16 v[72:75], v[100:103], v[138:141], v[72:75]
	s_waitcnt lgkmcnt(1)
	v_mfma_f32_16x16x32_bf16 v[68:71], v[100:103], v[212:215], v[68:71]
	s_waitcnt lgkmcnt(0)
	v_mfma_f32_16x16x32_bf16 v[64:67], v[100:103], v[216:219], v[64:67]
	s_cbranch_vccnz .LBB0_103
	s_mov_b64 s[4:5], 0
